# MLA attention PV phase: the V2 half-0 fragment gets its own registers and all five V fragment reads are issued together, counted lgkmcnt ladder instead of read-then-lgkmcnt(0) before the MFMA, on top
# baseline (speedup 1.0000x reference)
.LBB0_436:
	v_add3_u32 v198, s20, v180, v182
	ds_read_b128 v[82:85], v198
	ds_read_b128 v[186:189], v198 offset:32
	s_mulk_i32 s24, 0x4800
	v_add_u32_e32 v221, s24, v185
	v_sub_f32_e32 v202, v2, v184
	s_waitcnt lgkmcnt(1)
	v_mfma_f32_32x32x16_bf16 v[82:97], v[82:85], v[98:101], 0
	v_sub_f32_e32 v203, v3, v184
	v_sub_f32_e32 v204, v4, v184
	v_sub_f32_e32 v205, v5, v184
	v_sub_f32_e32 v206, v6, v184
	v_sub_f32_e32 v207, v7, v184
	v_sub_f32_e32 v208, v8, v184
	v_sub_f32_e32 v209, v9, v184
	s_waitcnt lgkmcnt(0)
	v_mfma_f32_32x32x16_bf16 v[82:97], v[186:189], v[102:105], v[82:97]
	ds_read_b128 v[186:189], v198 offset:64
	ds_read_b128 v[190:193], v198 offset:96
	v_exp_f32_e32 v217, v202
	v_exp_f32_e32 v218, v203
	v_exp_f32_e32 v219, v204
	v_exp_f32_e32 v220, v205
	v_exp_f32_e32 v206, v206
	v_exp_f32_e32 v207, v207
	s_waitcnt lgkmcnt(1)
	v_mfma_f32_32x32x16_bf16 v[82:97], v[186:189], v[106:109], v[82:97]
	v_exp_f32_e32 v208, v208
	v_exp_f32_e32 v209, v209
	v_sub_f32_e32 v210, v10, v184
	v_sub_f32_e32 v211, v11, v184
	v_sub_f32_e32 v212, v12, v184
	v_sub_f32_e32 v213, v13, v184
	v_sub_f32_e32 v214, v14, v184
	s_waitcnt lgkmcnt(0)
	v_mfma_f32_32x32x16_bf16 v[82:97], v[190:193], v[110:113], v[82:97]
	ds_read_b128 v[186:189], v198 offset:128
	ds_read_b128 v[190:193], v198 offset:160
	v_sub_f32_e32 v215, v15, v184
	v_sub_f32_e32 v216, v16, v184
	v_exp_f32_e32 v210, v210
	v_exp_f32_e32 v211, v211
	v_exp_f32_e32 v212, v212
	v_exp_f32_e32 v213, v213
	s_waitcnt lgkmcnt(1)
	v_mfma_f32_32x32x16_bf16 v[82:97], v[186:189], v[114:117], v[82:97]
	ds_read_b128 v[186:189], v198 offset:192
	v_exp_f32_e32 v214, v214
	v_exp_f32_e32 v215, v215
	v_exp_f32_e32 v216, v216
	v_max_f32_e32 v2, v2, v3
	s_waitcnt lgkmcnt(1)
	v_mfma_f32_32x32x16_bf16 v[82:97], v[190:193], v[118:121], v[82:97]
	ds_read_b128 v[190:193], v198 offset:224
	v_max3_f32 v2, v2, v4, v5
	v_max3_f32 v2, v2, v6, v7
	v_max3_f32 v2, v2, v8, v9
	v_max3_f32 v6, v2, v10, v11
	v_max3_f32 v6, v6, v12, v13
	v_max3_f32 v6, v6, v14, v15
	s_waitcnt lgkmcnt(1)
	v_mfma_f32_32x32x16_bf16 v[82:97], v[186:189], v[122:125], v[82:97]
	ds_read_b128 v[186:189], v198 offset:256
	v_max3_f32 v10, v6, v16, v17
	v_add_f32_e32 v12, v218, v217
	ds_bpermute_b32 v11, v178, v10
	s_waitcnt lgkmcnt(2)
	v_mfma_f32_32x32x16_bf16 v[82:97], v[190:193], v[126:129], v[82:97]
	ds_read_b128 v[190:193], v198 offset:288
	ds_read_b128 v[194:197], v198 offset:320
	ds_read_b128 v[198:201], v198 offset:352
	s_waitcnt lgkmcnt(4)
	v_mfma_f32_32x32x16_bf16 v[82:97], v[186:189], v[130:133], v[82:97]
	ds_read_b128 v[186:189], v221 offset:51264
	s_waitcnt lgkmcnt(3)
	v_mfma_f32_32x32x16_bf16 v[82:97], v[190:193], v[134:137], v[82:97]
	ds_read_b128 v[190:193], v221 offset:51296
	s_waitcnt lgkmcnt(3)
	v_mfma_f32_32x32x16_bf16 v[82:97], v[194:197], v[138:141], v[82:97]
	v_cvt_pk_bf16_f32 v194, v217, v218
	v_cvt_pk_bf16_f32 v195, v219, v220
	v_cvt_pk_bf16_f32 v196, v206, v207
	v_cvt_pk_bf16_f32 v197, v208, v209
	s_waitcnt lgkmcnt(1)
	s_nop 0
	v_mfma_f32_32x32x16_bf16 v[18:33], v[186:189], v[194:197], v[18:33]
	v_sub_f32_e32 v186, v17, v184
	v_exp_f32_e32 v222, v186
	v_cvt_pk_bf16_f32 v186, v210, v211
	v_cvt_pk_bf16_f32 v187, v212, v213
	v_cvt_pk_bf16_f32 v188, v214, v215
	v_cvt_pk_bf16_f32 v189, v216, v222
	s_waitcnt lgkmcnt(0)
	s_nop 0
	v_mfma_f32_32x32x16_bf16 v[18:33], v[190:193], v[186:189], v[18:33]
	ds_read_b128 v[190:193], v221 offset:55872
	ds_read_b128 v[202:205], v221 offset:55904
	ds_read_b128 v[236:239], v221 offset:60480
	ds_read_b128 v[2:5], v221 offset:60512
	ds_read_b128 v[6:9], v221 offset:65088
	s_waitcnt lgkmcnt(4)
	v_mfma_f32_32x32x16_bf16 v[34:49], v[190:193], v[194:197], v[34:49]
	ds_read_b128 v[190:193], v221 offset:65120
	s_waitcnt lgkmcnt(4)
	v_mfma_f32_32x32x16_bf16 v[34:49], v[202:205], v[186:189], v[34:49]
	s_waitcnt lgkmcnt(3)
	v_mfma_f32_32x32x16_bf16 v[50:65], v[236:239], v[194:197], v[50:65]
	s_waitcnt lgkmcnt(2)
	v_mfma_f32_32x32x16_bf16 v[50:65], v[2:5], v[186:189], v[50:65]
	v_add_f32_e32 v2, v219, v12
	v_add_f32_e32 v2, v220, v2
	v_add_f32_e32 v2, v206, v2
	v_add_f32_e32 v2, v207, v2
	v_add_f32_e32 v2, v208, v2
	v_add_f32_e32 v12, v209, v2
	s_waitcnt lgkmcnt(1)
	v_mfma_f32_32x32x16_bf16 v[66:81], v[6:9], v[194:197], v[66:81]
	v_add_f32_e32 v6, v210, v12
	v_add_f32_e32 v6, v211, v6
	v_add_f32_e32 v6, v212, v6
	v_add_f32_e32 v6, v213, v6
	v_add_f32_e32 v6, v214, v6
	v_add_f32_e32 v6, v215, v6
	v_add_f32_e32 v6, v216, v6
	s_waitcnt lgkmcnt(0)
	v_mfma_f32_32x32x16_bf16 v[66:81], v[190:193], v[186:189], v[66:81]
	v_add_f32_e32 v2, v222, v6
	v_add_f32_e32 v183, v183, v2
	v_max_f32_e32 v186, v10, v11
	v_sub_f32_e32 v202, v186, v184
	v_cmp_lt_f32_e32 vcc, s2, v202
	v_mfma_f32_32x32x16_bf16 v[2:17], v[198:201], v[142:145], v[82:97]
	s_cbranch_vccz .LBB0_438
	v_max_f32_e32 v202, v202, v202
	v_max_f32_e32 v203, 0, v202
	v_exp_f32_e64 v202, -v203
	v_add_f32_e32 v184, v184, v203
	v_mul_f32_e32 v183, v183, v202
	v_pk_mul_f32 v[32:33], v[202:203], v[32:33] op_sel_hi:[0,1]
	v_pk_mul_f32 v[30:31], v[202:203], v[30:31] op_sel_hi:[0,1]
	v_pk_mul_f32 v[28:29], v[202:203], v[28:29] op_sel_hi:[0,1]
	v_pk_mul_f32 v[26:27], v[202:203], v[26:27] op_sel_hi:[0,1]
	v_pk_mul_f32 v[24:25], v[202:203], v[24:25] op_sel_hi:[0,1]
	v_pk_mul_f32 v[22:23], v[202:203], v[22:23] op_sel_hi:[0,1]
	v_pk_mul_f32 v[20:21], v[202:203], v[20:21] op_sel_hi:[0,1]
	v_pk_mul_f32 v[18:19], v[202:203], v[18:19] op_sel_hi:[0,1]
	v_pk_mul_f32 v[48:49], v[202:203], v[48:49] op_sel_hi:[0,1]
	v_pk_mul_f32 v[46:47], v[202:203], v[46:47] op_sel_hi:[0,1]
	v_pk_mul_f32 v[44:45], v[202:203], v[44:45] op_sel_hi:[0,1]
	v_pk_mul_f32 v[42:43], v[202:203], v[42:43] op_sel_hi:[0,1]
	v_pk_mul_f32 v[40:41], v[202:203], v[40:41] op_sel_hi:[0,1]
	v_pk_mul_f32 v[38:39], v[202:203], v[38:39] op_sel_hi:[0,1]
	v_pk_mul_f32 v[36:37], v[202:203], v[36:37] op_sel_hi:[0,1]
	v_pk_mul_f32 v[34:35], v[202:203], v[34:35] op_sel_hi:[0,1]
	v_pk_mul_f32 v[64:65], v[202:203], v[64:65] op_sel_hi:[0,1]
	v_pk_mul_f32 v[62:63], v[202:203], v[62:63] op_sel_hi:[0,1]
	v_pk_mul_f32 v[60:61], v[202:203], v[60:61] op_sel_hi:[0,1]
	v_pk_mul_f32 v[58:59], v[202:203], v[58:59] op_sel_hi:[0,1]
	v_pk_mul_f32 v[56:57], v[202:203], v[56:57] op_sel_hi:[0,1]
	v_pk_mul_f32 v[54:55], v[202:203], v[54:55] op_sel_hi:[0,1]
	v_pk_mul_f32 v[52:53], v[202:203], v[52:53] op_sel_hi:[0,1]
	v_pk_mul_f32 v[50:51], v[202:203], v[50:51] op_sel_hi:[0,1]
	v_pk_mul_f32 v[80:81], v[202:203], v[80:81] op_sel_hi:[0,1]
	v_pk_mul_f32 v[78:79], v[202:203], v[78:79] op_sel_hi:[0,1]
	v_pk_mul_f32 v[76:77], v[202:203], v[76:77] op_sel_hi:[0,1]
	v_pk_mul_f32 v[74:75], v[202:203], v[74:75] op_sel_hi:[0,1]
	v_pk_mul_f32 v[72:73], v[202:203], v[72:73] op_sel_hi:[0,1]
	v_pk_mul_f32 v[70:71], v[202:203], v[70:71] op_sel_hi:[0,1]
	v_pk_mul_f32 v[68:69], v[202:203], v[68:69] op_sel_hi:[0,1]
	v_pk_mul_f32 v[66:67], v[202:203], v[66:67] op_sel_hi:[0,1]

.LBB0_443:
	v_add3_u32 v198, s20, v180, v182
	ds_read_b128 v[82:85], v198 offset:12800
	ds_read_b128 v[186:189], v198 offset:12832
	s_mul_i32 s12, s19, 0x4800
	v_add_u32_e32 v221, s12, v185
	v_sub_f32_e32 v202, v2, v184
	s_waitcnt lgkmcnt(1)
	v_mfma_f32_32x32x16_bf16 v[82:97], v[82:85], v[98:101], 0
	v_sub_f32_e32 v203, v3, v184
	v_sub_f32_e32 v204, v4, v184
	v_sub_f32_e32 v205, v5, v184
	v_sub_f32_e32 v206, v6, v184
	v_sub_f32_e32 v207, v7, v184
	v_sub_f32_e32 v208, v8, v184
	v_sub_f32_e32 v209, v9, v184
	s_waitcnt lgkmcnt(0)
	v_mfma_f32_32x32x16_bf16 v[82:97], v[186:189], v[102:105], v[82:97]
	ds_read_b128 v[186:189], v198 offset:12864
	ds_read_b128 v[190:193], v198 offset:12896
	v_exp_f32_e32 v217, v202
	v_exp_f32_e32 v218, v203
	v_exp_f32_e32 v219, v204
	v_exp_f32_e32 v220, v205
	v_exp_f32_e32 v206, v206
	v_exp_f32_e32 v207, v207
	s_waitcnt lgkmcnt(1)
	v_mfma_f32_32x32x16_bf16 v[82:97], v[186:189], v[106:109], v[82:97]
	v_exp_f32_e32 v208, v208
	v_exp_f32_e32 v209, v209
	v_sub_f32_e32 v210, v10, v184
	v_sub_f32_e32 v211, v11, v184
	v_sub_f32_e32 v212, v12, v184
	v_sub_f32_e32 v213, v13, v184
	v_sub_f32_e32 v214, v14, v184
	s_waitcnt lgkmcnt(0)
	v_mfma_f32_32x32x16_bf16 v[82:97], v[190:193], v[110:113], v[82:97]
	ds_read_b128 v[186:189], v198 offset:12928
	ds_read_b128 v[190:193], v198 offset:12960
	v_sub_f32_e32 v215, v15, v184
	v_sub_f32_e32 v216, v16, v184
	v_exp_f32_e32 v210, v210
	v_exp_f32_e32 v211, v211
	v_exp_f32_e32 v212, v212
	v_exp_f32_e32 v213, v213
	s_waitcnt lgkmcnt(1)
	v_mfma_f32_32x32x16_bf16 v[82:97], v[186:189], v[114:117], v[82:97]
	ds_read_b128 v[186:189], v198 offset:12992
	v_exp_f32_e32 v214, v214
	v_exp_f32_e32 v215, v215
	v_exp_f32_e32 v216, v216
	v_max_f32_e32 v2, v2, v3
	s_waitcnt lgkmcnt(1)
	v_mfma_f32_32x32x16_bf16 v[82:97], v[190:193], v[118:121], v[82:97]
	ds_read_b128 v[190:193], v198 offset:13024
	v_max3_f32 v2, v2, v4, v5
	v_max3_f32 v2, v2, v6, v7
	v_max3_f32 v2, v2, v8, v9
	v_max3_f32 v6, v2, v10, v11
	v_max3_f32 v6, v6, v12, v13
	v_max3_f32 v6, v6, v14, v15
	s_waitcnt lgkmcnt(1)
	v_mfma_f32_32x32x16_bf16 v[82:97], v[186:189], v[122:125], v[82:97]
	ds_read_b128 v[186:189], v198 offset:13056
	v_max3_f32 v10, v6, v16, v17
	v_add_f32_e32 v12, v218, v217
	ds_bpermute_b32 v11, v178, v10
	s_waitcnt lgkmcnt(2)
	v_mfma_f32_32x32x16_bf16 v[82:97], v[190:193], v[126:129], v[82:97]
	ds_read_b128 v[190:193], v198 offset:13088
	ds_read_b128 v[194:197], v198 offset:13120
	ds_read_b128 v[198:201], v198 offset:13152
	s_waitcnt lgkmcnt(4)
	v_mfma_f32_32x32x16_bf16 v[82:97], v[186:189], v[130:133], v[82:97]
	ds_read_b128 v[186:189], v221 offset:51200
	s_waitcnt lgkmcnt(3)
	v_mfma_f32_32x32x16_bf16 v[82:97], v[190:193], v[134:137], v[82:97]
	ds_read_b128 v[190:193], v221 offset:51232
	s_waitcnt lgkmcnt(3)
	v_mfma_f32_32x32x16_bf16 v[82:97], v[194:197], v[138:141], v[82:97]
	v_cvt_pk_bf16_f32 v194, v217, v218
	v_cvt_pk_bf16_f32 v195, v219, v220
	v_cvt_pk_bf16_f32 v196, v206, v207
	v_cvt_pk_bf16_f32 v197, v208, v209
	s_waitcnt lgkmcnt(1)
	s_nop 0
	v_mfma_f32_32x32x16_bf16 v[18:33], v[186:189], v[194:197], v[18:33]
	v_sub_f32_e32 v186, v17, v184
	v_exp_f32_e32 v222, v186
	v_cvt_pk_bf16_f32 v186, v210, v211
	v_cvt_pk_bf16_f32 v187, v212, v213
	v_cvt_pk_bf16_f32 v188, v214, v215
	v_cvt_pk_bf16_f32 v189, v216, v222
	s_waitcnt lgkmcnt(0)
	s_nop 0
	v_mfma_f32_32x32x16_bf16 v[18:33], v[190:193], v[186:189], v[18:33]
	ds_read_b128 v[190:193], v221 offset:55808
	ds_read_b128 v[202:205], v221 offset:55840
	ds_read_b128 v[236:239], v221 offset:60416
	ds_read_b128 v[2:5], v221 offset:60448
	ds_read_b128 v[6:9], v221 offset:65024
	s_waitcnt lgkmcnt(4)
	v_mfma_f32_32x32x16_bf16 v[34:49], v[190:193], v[194:197], v[34:49]
	ds_read_b128 v[190:193], v221 offset:65056
	s_waitcnt lgkmcnt(4)
	v_mfma_f32_32x32x16_bf16 v[34:49], v[202:205], v[186:189], v[34:49]
	s_waitcnt lgkmcnt(3)
	v_mfma_f32_32x32x16_bf16 v[50:65], v[236:239], v[194:197], v[50:65]
	s_waitcnt lgkmcnt(2)
	v_mfma_f32_32x32x16_bf16 v[50:65], v[2:5], v[186:189], v[50:65]
	v_add_f32_e32 v2, v219, v12
	v_add_f32_e32 v2, v220, v2
	v_add_f32_e32 v2, v206, v2
	v_add_f32_e32 v2, v207, v2
	v_add_f32_e32 v2, v208, v2
	v_add_f32_e32 v12, v209, v2
	s_waitcnt lgkmcnt(1)
	v_mfma_f32_32x32x16_bf16 v[66:81], v[6:9], v[194:197], v[66:81]
	v_add_f32_e32 v6, v210, v12
	v_add_f32_e32 v6, v211, v6
	v_add_f32_e32 v6, v212, v6
	v_add_f32_e32 v6, v213, v6
	v_add_f32_e32 v6, v214, v6
	v_add_f32_e32 v6, v215, v6
	v_add_f32_e32 v6, v216, v6
	s_waitcnt lgkmcnt(0)
	v_mfma_f32_32x32x16_bf16 v[66:81], v[190:193], v[186:189], v[66:81]
	v_add_f32_e32 v2, v222, v6
	v_add_f32_e32 v183, v183, v2
	v_max_f32_e32 v186, v10, v11
	v_sub_f32_e32 v202, v186, v184
	v_cmp_lt_f32_e32 vcc, s2, v202
	v_mfma_f32_32x32x16_bf16 v[2:17], v[198:201], v[142:145], v[82:97]
	s_cbranch_vccz .LBB0_445
	v_max_f32_e32 v202, v202, v202
	v_max_f32_e32 v203, 0, v202
	v_exp_f32_e64 v202, -v203
	v_add_f32_e32 v184, v184, v203
	v_mul_f32_e32 v183, v183, v202
	v_pk_mul_f32 v[32:33], v[32:33], v[202:203] op_sel_hi:[1,0]
	v_pk_mul_f32 v[30:31], v[30:31], v[202:203] op_sel_hi:[1,0]
	v_pk_mul_f32 v[28:29], v[28:29], v[202:203] op_sel_hi:[1,0]
	v_pk_mul_f32 v[26:27], v[26:27], v[202:203] op_sel_hi:[1,0]
	v_pk_mul_f32 v[24:25], v[24:25], v[202:203] op_sel_hi:[1,0]
	v_pk_mul_f32 v[22:23], v[22:23], v[202:203] op_sel_hi:[1,0]
	v_pk_mul_f32 v[20:21], v[20:21], v[202:203] op_sel_hi:[1,0]
	v_pk_mul_f32 v[18:19], v[18:19], v[202:203] op_sel_hi:[1,0]
	v_pk_mul_f32 v[48:49], v[202:203], v[48:49] op_sel_hi:[0,1]
	v_pk_mul_f32 v[46:47], v[202:203], v[46:47] op_sel_hi:[0,1]
	v_pk_mul_f32 v[44:45], v[202:203], v[44:45] op_sel_hi:[0,1]
	v_pk_mul_f32 v[42:43], v[202:203], v[42:43] op_sel_hi:[0,1]
	v_pk_mul_f32 v[40:41], v[202:203], v[40:41] op_sel_hi:[0,1]
	v_pk_mul_f32 v[38:39], v[202:203], v[38:39] op_sel_hi:[0,1]
	v_pk_mul_f32 v[36:37], v[202:203], v[36:37] op_sel_hi:[0,1]
	v_pk_mul_f32 v[34:35], v[202:203], v[34:35] op_sel_hi:[0,1]
	v_pk_mul_f32 v[64:65], v[202:203], v[64:65] op_sel_hi:[0,1]
	v_pk_mul_f32 v[62:63], v[202:203], v[62:63] op_sel_hi:[0,1]
	v_pk_mul_f32 v[60:61], v[202:203], v[60:61] op_sel_hi:[0,1]
	v_pk_mul_f32 v[58:59], v[202:203], v[58:59] op_sel_hi:[0,1]
	v_pk_mul_f32 v[56:57], v[202:203], v[56:57] op_sel_hi:[0,1]
	v_pk_mul_f32 v[54:55], v[202:203], v[54:55] op_sel_hi:[0,1]
	v_pk_mul_f32 v[52:53], v[202:203], v[52:53] op_sel_hi:[0,1]
	v_pk_mul_f32 v[50:51], v[202:203], v[50:51] op_sel_hi:[0,1]
	v_pk_mul_f32 v[80:81], v[202:203], v[80:81] op_sel_hi:[0,1]
	v_pk_mul_f32 v[78:79], v[202:203], v[78:79] op_sel_hi:[0,1]
	v_pk_mul_f32 v[76:77], v[202:203], v[76:77] op_sel_hi:[0,1]
	v_pk_mul_f32 v[74:75], v[202:203], v[74:75] op_sel_hi:[0,1]
	v_pk_mul_f32 v[72:73], v[202:203], v[72:73] op_sel_hi:[0,1]
	v_pk_mul_f32 v[70:71], v[202:203], v[70:71] op_sel_hi:[0,1]
	v_pk_mul_f32 v[68:69], v[202:203], v[68:69] op_sel_hi:[0,1]
	v_pk_mul_f32 v[66:67], v[202:203], v[66:67] op_sel_hi:[0,1]
